# MLA up-proj GEMMs rebalanced (WG index rotated by G/2 for k/v), K-prep loop: three k_nope loads hoisted with counted waits
# baseline (speedup 1.0000x reference)
.LBB0_891:
	global_load_dwordx2 v[14:15], v[10:11], off offset:-512
	global_load_ushort v32, v[8:9], off
	global_load_ushort v33, v[8:9], off offset:32
	global_load_dword v28, v113, s[10:11]
	global_load_dwordx2 v[40:41], v[10:11], off
	global_load_dwordx2 v[42:43], v[10:11], off offset:512
	s_ashr_i32 s12, s6, 14
	s_mul_i32 s12, s12, 12
	v_or_b32_e32 v24, s12, v16
	v_ashrrev_i32_e32 v25, 31, v24
	s_and_b32 s7, s6, 0x3fff
	v_lshlrev_b64 v[24:25], 14, v[24:25]
	v_mov_b64_e32 v[12:13], s[8:9]
	v_or_b32_e32 v24, s7, v24
	v_mad_u64_u32 v[26:27], s[14:15], v24, s94, v[12:13]
	v_mad_i32_i24 v27, v25, s94, v27
	v_lshl_add_u64 v[24:25], v[26:27], 0, v[112:113]
	v_lshl_add_u64 v[26:27], v[26:27], 0, v[6:7]
	s_add_i32 s6, s6, s28
	s_add_u32 s10, s10, s62
	s_addc_u32 s11, s11, s63
	v_lshl_add_u64 v[8:9], v[8:9], 0, s[50:51]
	s_cmpk_gt_i32 s6, 0x7fff
	s_waitcnt vmcnt(5)
	v_and_b32_e32 v29, 0xffff0000, v15
	v_and_b32_e32 v31, 0xffff0000, v14
	v_lshlrev_b32_e32 v30, 16, v14
	s_waitcnt vmcnt(2)
	v_cvt_f32_i32_e32 v38, v28
	v_lshlrev_b32_e32 v28, 16, v15
	v_lshlrev_b32_e32 v15, 16, v33
	v_lshlrev_b32_e32 v14, 16, v32
	v_mov_b32_e32 v36, v15
	v_mov_b32_e32 v37, v31
	v_pk_mul_f32 v[32:33], v[28:29], v[28:29]
	v_mov_b32_e32 v34, v14
	v_mov_b32_e32 v35, v30
	v_pk_mul_f32 v[36:37], v[36:37], v[36:37]
	v_add_f32_e32 v39, v32, v33
	v_pk_fma_f32 v[32:33], v[34:35], v[34:35], v[36:37]
	v_mul_f32_e32 v34, v17, v38
	v_add_f32_e32 v33, v33, v39
	v_add_f32_e32 v33, v32, v33
	ds_bpermute_b32 v38, v18, v33
	v_cvt_f64_f32_e32 v[34:35], v34
	v_mul_f64 v[36:37], v[34:35], s[48:49]
	v_rndne_f64_e32 v[36:37], v[36:37]
	v_fma_f64 v[34:35], v[34:35], s[48:49], -v[36:37]
	v_cvt_f32_f64_e32 v35, v[34:35]
	s_waitcnt lgkmcnt(0)
	v_add_f32_e32 v33, v33, v38
	v_sin_f32_e32 v34, v35
	v_cos_f32_e32 v36, v35
	ds_bpermute_b32 v35, v19, v33
	s_waitcnt lgkmcnt(0)
	v_add_f32_e32 v33, v33, v35
	ds_bpermute_b32 v35, v20, v33
	s_waitcnt lgkmcnt(0)
	v_add_f32_e32 v33, v33, v35
	ds_bpermute_b32 v35, v21, v33
	s_waitcnt lgkmcnt(0)
	v_add_f32_e32 v33, v33, v35
	v_fmamk_f32 v33, v33, 0x3c2aaaab, v229
	v_mul_f32_e32 v35, 0x4b800000, v33
	v_cmp_gt_f32_e32 vcc, s65, v33
	s_nop 1
	v_cndmask_b32_e32 v33, v33, v35, vcc
	v_rsq_f32_e32 v33, v33
	s_nop 0
	v_mul_f32_e32 v35, 0x45800000, v33
	v_cndmask_b32_e32 v38, v33, v35, vcc
	v_pk_mul_f32 v[30:31], v[38:39], v[30:31] op_sel_hi:[0,1]
	v_pk_mul_f32 v[28:29], v[38:39], v[28:29] op_sel_hi:[0,1]
	v_pk_mul_f32 v[38:39], v[38:39], v[14:15] op_sel_hi:[0,1]
	v_pk_mul_f32 v[30:31], v[0:1], v[30:31]
	v_pk_mul_f32 v[28:29], v[2:3], v[28:29]
	v_pk_mul_f32 v[38:39], v[4:5], v[38:39]
	v_cvt_pk_bf16_f32 v30, v30, v31
	v_cvt_pk_bf16_f32 v31, v28, v29
	v_pk_mul_f32 v[28:29], v[34:35], v[38:39] op_sel_hi:[0,1]
	global_store_dwordx2 v[24:25], v[30:31], off
	v_pk_fma_f32 v[24:25], v[36:37], v[38:39], v[28:29] op_sel:[0,0,1] op_sel_hi:[1,1,0] neg_lo:[0,0,1] neg_hi:[0,0,1]
	v_pk_fma_f32 v[28:29], v[36:37], v[38:39], v[28:29] op_sel:[0,0,1] op_sel_hi:[0,1,0]
	v_cvt_pk_bf16_f32 v24, v24, v29
	global_store_short v[26:27], v24, off offset:128
	global_store_short_d16_hi v[26:27], v24, off offset:160
	v_add_u32_e32 v26, s12, v22
	v_ashrrev_i32_e32 v27, 31, v26
	v_lshlrev_b64 v[26:27], 14, v[26:27]
	v_or_b32_e32 v26, s7, v26
	v_mad_u64_u32 v[28:29], s[14:15], v26, s94, v[12:13]
	v_mad_i32_i24 v29, v27, s94, v29
	v_lshl_add_u64 v[26:27], v[28:29], 0, v[112:113]
	v_lshl_add_u64 v[28:29], v[28:29], 0, v[6:7]
	s_waitcnt vmcnt(4)
	v_and_b32_e32 v31, 0xffff0000, v41
	v_and_b32_e32 v39, 0xffff0000, v40
	v_lshlrev_b32_e32 v30, 16, v41
	v_lshlrev_b32_e32 v38, 16, v40
	v_mov_b32_e32 v40, v39
	v_mov_b32_e32 v41, v31
	v_mov_b32_e32 v24, v38
	v_mov_b32_e32 v25, v30
	v_pk_mul_f32 v[40:41], v[40:41], v[40:41]
	s_nop 0
	v_pk_fma_f32 v[24:25], v[24:25], v[24:25], v[40:41]
	s_nop 0
	v_add_f32_e32 v24, v24, v25
	v_add_f32_e32 v24, v32, v24
	ds_bpermute_b32 v25, v18, v24
	s_waitcnt lgkmcnt(0)
	v_add_f32_e32 v24, v24, v25
	ds_bpermute_b32 v25, v19, v24
	s_waitcnt lgkmcnt(0)
	v_add_f32_e32 v24, v24, v25
	ds_bpermute_b32 v25, v20, v24
	s_waitcnt lgkmcnt(0)
	v_add_f32_e32 v24, v24, v25
	ds_bpermute_b32 v25, v21, v24
	s_waitcnt lgkmcnt(0)
	v_add_f32_e32 v24, v24, v25
	v_fmamk_f32 v24, v24, 0x3c2aaaab, v229
	v_mul_f32_e32 v25, 0x4b800000, v24
	v_cmp_gt_f32_e32 vcc, s65, v24
	s_nop 1
	v_cndmask_b32_e32 v24, v24, v25, vcc
	v_rsq_f32_e32 v24, v24
	s_nop 0
	v_mul_f32_e32 v25, 0x45800000, v24
	v_cndmask_b32_e32 v24, v24, v25, vcc
	v_pk_mul_f32 v[38:39], v[24:25], v[38:39] op_sel_hi:[0,1]
	v_pk_mul_f32 v[30:31], v[24:25], v[30:31] op_sel_hi:[0,1]
	v_pk_mul_f32 v[24:25], v[24:25], v[14:15] op_sel_hi:[0,1]
	v_pk_mul_f32 v[38:39], v[0:1], v[38:39]
	v_pk_mul_f32 v[30:31], v[2:3], v[30:31]
	v_pk_mul_f32 v[24:25], v[4:5], v[24:25]
	v_cvt_pk_bf16_f32 v38, v38, v39
	v_cvt_pk_bf16_f32 v39, v30, v31
	v_pk_mul_f32 v[30:31], v[34:35], v[24:25] op_sel_hi:[0,1]
	global_store_dwordx2 v[26:27], v[38:39], off
	v_pk_fma_f32 v[26:27], v[36:37], v[24:25], v[30:31] op_sel:[0,0,1] op_sel_hi:[1,1,0] neg_lo:[0,0,1] neg_hi:[0,0,1]
	v_pk_fma_f32 v[24:25], v[36:37], v[24:25], v[30:31] op_sel:[0,0,1] op_sel_hi:[0,1,0]
	v_cvt_pk_bf16_f32 v24, v26, v25
	global_store_short v[28:29], v24, off offset:128
	global_store_short_d16_hi v[28:29], v24, off offset:160
	v_add_u32_e32 v26, s12, v23
	v_ashrrev_i32_e32 v27, 31, v26
	v_lshlrev_b64 v[26:27], 14, v[26:27]
	v_or_b32_e32 v26, s7, v26
	v_mad_u64_u32 v[12:13], s[12:13], v26, s94, v[12:13]
	v_mad_i32_i24 v13, v27, s94, v13
	v_lshl_add_u64 v[26:27], v[12:13], 0, v[112:113]
	v_lshl_add_u64 v[12:13], v[12:13], 0, v[6:7]
	v_lshl_add_u64 v[10:11], v[10:11], 0, s[96:97]
	s_waitcnt vmcnt(6)
	v_and_b32_e32 v29, 0xffff0000, v43
	v_and_b32_e32 v31, 0xffff0000, v42
	v_lshlrev_b32_e32 v28, 16, v43
	v_lshlrev_b32_e32 v30, 16, v42
	v_mov_b32_e32 v38, v31
	v_mov_b32_e32 v39, v29
	v_mov_b32_e32 v24, v30
	v_mov_b32_e32 v25, v28
	v_pk_mul_f32 v[38:39], v[38:39], v[38:39]
	s_nop 0
	v_pk_fma_f32 v[24:25], v[24:25], v[24:25], v[38:39]
	s_nop 0
	v_add_f32_e32 v24, v24, v25
	v_add_f32_e32 v24, v32, v24
	ds_bpermute_b32 v25, v18, v24
	s_waitcnt lgkmcnt(0)
	v_add_f32_e32 v24, v24, v25
	ds_bpermute_b32 v25, v19, v24
	s_waitcnt lgkmcnt(0)
	v_add_f32_e32 v24, v24, v25
	ds_bpermute_b32 v25, v20, v24
	s_waitcnt lgkmcnt(0)
	v_add_f32_e32 v24, v24, v25
	ds_bpermute_b32 v25, v21, v24
	s_waitcnt lgkmcnt(0)
	v_add_f32_e32 v24, v24, v25
	v_fmamk_f32 v24, v24, 0x3c2aaaab, v229
	v_mul_f32_e32 v25, 0x4b800000, v24
	v_cmp_gt_f32_e32 vcc, s65, v24
	s_nop 1
	v_cndmask_b32_e32 v24, v24, v25, vcc
	v_rsq_f32_e32 v24, v24
	s_nop 0
	v_mul_f32_e32 v25, 0x45800000, v24
	v_cndmask_b32_e32 v24, v24, v25, vcc
	v_pk_mul_f32 v[30:31], v[24:25], v[30:31] op_sel_hi:[0,1]
	v_pk_mul_f32 v[28:29], v[24:25], v[28:29] op_sel_hi:[0,1]
	v_pk_mul_f32 v[14:15], v[24:25], v[14:15] op_sel_hi:[0,1]
	v_pk_mul_f32 v[24:25], v[0:1], v[30:31]
	v_pk_mul_f32 v[28:29], v[2:3], v[28:29]
	v_pk_mul_f32 v[14:15], v[4:5], v[14:15]
	v_cvt_pk_bf16_f32 v24, v24, v25
	v_cvt_pk_bf16_f32 v25, v28, v29
	v_pk_mul_f32 v[28:29], v[34:35], v[14:15] op_sel_hi:[0,1]
	global_store_dwordx2 v[26:27], v[24:25], off
	v_pk_fma_f32 v[24:25], v[36:37], v[14:15], v[28:29] op_sel:[0,0,1] op_sel_hi:[1,1,0] neg_lo:[0,0,1] neg_hi:[0,0,1]
	v_pk_fma_f32 v[14:15], v[36:37], v[14:15], v[28:29] op_sel:[0,0,1] op_sel_hi:[0,1,0]
	v_cvt_pk_bf16_f32 v14, v24, v15
	global_store_short v[12:13], v14, off offset:128
	global_store_short_d16_hi v[12:13], v14, off offset:160
	s_cbranch_scc0 .LBB0_891
